# e18: late_convert(rec_w_in) in the P5 tail loads 32-deep, masked lanes zero-filled, scale kept (on top of e14+e15+e17)
# speedup vs baseline: 1.0069x; 1.0037x over previous
.Le18_rd:
	s_waitcnt lgkmcnt(0)
	ds_read2_b32 v[6:7], v41 offset1:33
	s_waitcnt lgkmcnt(0)
	v_cvt_pk_bf16_f32 v52, v6, v7
	ds_read2_b32 v[6:7], v41 offset0:66 offset1:99
	v_add_u32_e32 v56, s16, v40
	s_waitcnt lgkmcnt(0)
	v_cvt_pk_bf16_f32 v53, v6, v7
	ds_read2_b32 v[6:7], v41 offset0:132 offset1:165
	s_ashr_i32 s7, s6, 31
	v_ashrrev_i32_e32 v57, 31, v56
	s_waitcnt lgkmcnt(0)
	v_cvt_pk_bf16_f32 v54, v6, v7
	ds_read2_b32 v[6:7], v41 offset0:198 offset1:231
	v_lshl_add_u64 v[58:59], s[6:7], 1, v[4:5]
	v_lshlrev_b64 v[60:61], 13, v[56:57]
	s_waitcnt lgkmcnt(0)
	v_cvt_pk_bf16_f32 v55, v6, v7
	ds_read2_b32 v[6:7], v41 offset0:8 offset1:41
	v_lshl_add_u64 v[60:61], v[58:59], 0, v[60:61]
	global_store_dwordx4 v[60:61], v[52:55], off
	v_add_u32_e32 v60, 8, v56
	v_ashrrev_i32_e32 v61, 31, v60
	s_waitcnt lgkmcnt(0)
	v_cvt_pk_bf16_f32 v52, v6, v7
	ds_read2_b32 v[6:7], v41 offset0:74 offset1:107
	s_waitcnt lgkmcnt(0)
	v_cvt_pk_bf16_f32 v53, v6, v7
	ds_read2_b32 v[6:7], v41 offset0:140 offset1:173
	s_waitcnt lgkmcnt(0)
	v_cvt_pk_bf16_f32 v54, v6, v7
	ds_read2_b32 v[6:7], v41 offset0:206 offset1:239
	v_lshlrev_b64 v[60:61], 13, v[60:61]
	s_waitcnt lgkmcnt(0)
	v_cvt_pk_bf16_f32 v55, v6, v7
	ds_read2_b32 v[6:7], v41 offset0:16 offset1:49
	v_lshl_add_u64 v[60:61], v[58:59], 0, v[60:61]
	global_store_dwordx4 v[60:61], v[52:55], off
	v_add_u32_e32 v60, 16, v56
	v_ashrrev_i32_e32 v61, 31, v60
	s_waitcnt lgkmcnt(0)
	v_cvt_pk_bf16_f32 v52, v6, v7
	ds_read2_b32 v[6:7], v41 offset0:82 offset1:115
	s_waitcnt lgkmcnt(0)
	v_cvt_pk_bf16_f32 v53, v6, v7
	ds_read2_b32 v[6:7], v41 offset0:148 offset1:181
	s_waitcnt lgkmcnt(0)
	v_cvt_pk_bf16_f32 v54, v6, v7
	ds_read2_b32 v[6:7], v41 offset0:214 offset1:247
	v_lshlrev_b64 v[60:61], 13, v[60:61]
	v_add_u32_e32 v56, 24, v56
	s_waitcnt lgkmcnt(0)
	v_cvt_pk_bf16_f32 v55, v6, v7
	ds_read2_b32 v[6:7], v41 offset0:24 offset1:57
	v_lshl_add_u64 v[60:61], v[58:59], 0, v[60:61]
	v_ashrrev_i32_e32 v57, 31, v56
	global_store_dwordx4 v[60:61], v[52:55], off
	v_lshlrev_b64 v[56:57], 13, v[56:57]
	v_lshl_add_u64 v[56:57], v[58:59], 0, v[56:57]
	s_waitcnt lgkmcnt(0)
	v_cvt_pk_bf16_f32 v52, v6, v7
	ds_read2_b32 v[6:7], v41 offset0:90 offset1:123
	s_waitcnt lgkmcnt(0)
	v_cvt_pk_bf16_f32 v53, v6, v7
	ds_read2_b32 v[6:7], v41 offset0:156 offset1:189
	s_waitcnt lgkmcnt(0)
	v_cvt_pk_bf16_f32 v54, v6, v7
	ds_read2_b32 v[6:7], v41 offset0:222 offset1:255
	s_waitcnt lgkmcnt(0)
	v_cvt_pk_bf16_f32 v55, v6, v7
	global_store_dwordx4 v[56:57], v[52:55], off
	s_waitcnt lgkmcnt(0)
	s_add_i32 s10, s10, s11
	s_add_i32 s12, s12, s13
	s_cmpk_lt_i32 s10, 0x5a00
	s_cbranch_scc0 .LBB0_1000

.LBB0_968:
	s_or_b64 exec, exec, s[0:1]
	s_mul_i32 s0, s17, 0xfffffe98
	s_add_i32 s0, s10, s0
	s_cmp_lt_i32 s0, 48
	s_cselect_b64 s[0:1], -1, 0
	v_cmp_gt_i32_e32 vcc, 0, v2
	s_lshl_b32 s6, s17, 6
	v_cndmask_b32_e64 v51, 1.0, v42, s[0:1]
	s_waitcnt lgkmcnt(0)
	v_mov_b32_e32 v197, v43
	v_or_b32_e32 v196, s6, v8
	v_mul_u32_u24_e32 v196, 0xb080, v196
	v_lshl_add_u32 v196, v2, 2, v196
	v_mov_b32_e32 v164, 0
	v_mov_b32_e32 v165, 0
	v_mov_b32_e32 v166, 0
	v_mov_b32_e32 v167, 0
	v_mov_b32_e32 v168, 0
	v_mov_b32_e32 v169, 0
	v_mov_b32_e32 v170, 0
	v_mov_b32_e32 v171, 0
	v_mov_b32_e32 v172, 0
	v_mov_b32_e32 v173, 0
	v_mov_b32_e32 v174, 0
	v_mov_b32_e32 v175, 0
	v_mov_b32_e32 v176, 0
	v_mov_b32_e32 v177, 0
	v_mov_b32_e32 v178, 0
	v_mov_b32_e32 v179, 0
	v_mov_b32_e32 v180, 0
	v_mov_b32_e32 v181, 0
	v_mov_b32_e32 v182, 0
	v_mov_b32_e32 v183, 0
	v_mov_b32_e32 v184, 0
	v_mov_b32_e32 v185, 0
	v_mov_b32_e32 v186, 0
	v_mov_b32_e32 v187, 0
	v_mov_b32_e32 v188, 0
	v_mov_b32_e32 v189, 0
	v_mov_b32_e32 v190, 0
	v_mov_b32_e32 v191, 0
	v_mov_b32_e32 v192, 0
	v_mov_b32_e32 v193, 0
	v_mov_b32_e32 v194, 0
	v_mov_b32_e32 v195, 0
	s_mov_b64 s[8:9], exec
	s_andn2_b64 exec, exec, vcc
	s_cbranch_execz .Le18_wr
	global_load_dword v164, v196, s[66:67] nt
	v_add_u32_e32 v196, 0x16100, v196
	global_load_dword v165, v196, s[66:67] nt
	v_add_u32_e32 v196, 0x16100, v196
	global_load_dword v166, v196, s[66:67] nt
	v_add_u32_e32 v196, 0x16100, v196
	global_load_dword v167, v196, s[66:67] nt
	v_add_u32_e32 v196, 0x16100, v196
	global_load_dword v168, v196, s[66:67] nt
	v_add_u32_e32 v196, 0x16100, v196
	global_load_dword v169, v196, s[66:67] nt
	v_add_u32_e32 v196, 0x16100, v196
	global_load_dword v170, v196, s[66:67] nt
	v_add_u32_e32 v196, 0x16100, v196
	global_load_dword v171, v196, s[66:67] nt
	v_add_u32_e32 v196, 0x16100, v196
	global_load_dword v172, v196, s[66:67] nt
	v_add_u32_e32 v196, 0x16100, v196
	global_load_dword v173, v196, s[66:67] nt
	v_add_u32_e32 v196, 0x16100, v196
	global_load_dword v174, v196, s[66:67] nt
	v_add_u32_e32 v196, 0x16100, v196
	global_load_dword v175, v196, s[66:67] nt
	v_add_u32_e32 v196, 0x16100, v196
	global_load_dword v176, v196, s[66:67] nt
	v_add_u32_e32 v196, 0x16100, v196
	global_load_dword v177, v196, s[66:67] nt
	v_add_u32_e32 v196, 0x16100, v196
	global_load_dword v178, v196, s[66:67] nt
	v_add_u32_e32 v196, 0x16100, v196
	global_load_dword v179, v196, s[66:67] nt
	v_add_u32_e32 v196, 0x16100, v196
	global_load_dword v180, v196, s[66:67] nt
	v_add_u32_e32 v196, 0x16100, v196
	global_load_dword v181, v196, s[66:67] nt
	v_add_u32_e32 v196, 0x16100, v196
	global_load_dword v182, v196, s[66:67] nt
	v_add_u32_e32 v196, 0x16100, v196
	global_load_dword v183, v196, s[66:67] nt
	v_add_u32_e32 v196, 0x16100, v196
	global_load_dword v184, v196, s[66:67] nt
	v_add_u32_e32 v196, 0x16100, v196
	global_load_dword v185, v196, s[66:67] nt
	v_add_u32_e32 v196, 0x16100, v196
	global_load_dword v186, v196, s[66:67] nt
	v_add_u32_e32 v196, 0x16100, v196
	global_load_dword v187, v196, s[66:67] nt
	v_add_u32_e32 v196, 0x16100, v196
	global_load_dword v188, v196, s[66:67] nt
	v_add_u32_e32 v196, 0x16100, v196
	global_load_dword v189, v196, s[66:67] nt
	v_add_u32_e32 v196, 0x16100, v196
	global_load_dword v190, v196, s[66:67] nt
	v_add_u32_e32 v196, 0x16100, v196
	global_load_dword v191, v196, s[66:67] nt
	v_add_u32_e32 v196, 0x16100, v196
	global_load_dword v192, v196, s[66:67] nt
	v_add_u32_e32 v196, 0x16100, v196
	global_load_dword v193, v196, s[66:67] nt
	v_add_u32_e32 v196, 0x16100, v196
	global_load_dword v194, v196, s[66:67] nt
	v_add_u32_e32 v196, 0x16100, v196
	global_load_dword v195, v196, s[66:67] nt
.Le18_wr:
	s_mov_b64 exec, s[8:9]
	s_waitcnt vmcnt(30)
	v_mul_f32_e32 v164, v51, v164
	v_mul_f32_e32 v165, v51, v165
	ds_write2_b32 v197, v164, v165 offset1:66
	s_waitcnt vmcnt(28)
	v_mul_f32_e32 v166, v51, v166
	v_mul_f32_e32 v167, v51, v167
	ds_write2_b32 v197, v166, v167 offset0:132 offset1:198
	v_add_u32_e32 v197, 0x420, v197
	s_waitcnt vmcnt(26)
	v_mul_f32_e32 v168, v51, v168
	v_mul_f32_e32 v169, v51, v169
	ds_write2_b32 v197, v168, v169 offset1:66
	s_waitcnt vmcnt(24)
	v_mul_f32_e32 v170, v51, v170
	v_mul_f32_e32 v171, v51, v171
	ds_write2_b32 v197, v170, v171 offset0:132 offset1:198
	v_add_u32_e32 v197, 0x420, v197
	s_waitcnt vmcnt(22)
	v_mul_f32_e32 v172, v51, v172
	v_mul_f32_e32 v173, v51, v173
	ds_write2_b32 v197, v172, v173 offset1:66
	s_waitcnt vmcnt(20)
	v_mul_f32_e32 v174, v51, v174
	v_mul_f32_e32 v175, v51, v175
	ds_write2_b32 v197, v174, v175 offset0:132 offset1:198
	v_add_u32_e32 v197, 0x420, v197
	s_waitcnt vmcnt(18)
	v_mul_f32_e32 v176, v51, v176
	v_mul_f32_e32 v177, v51, v177
	ds_write2_b32 v197, v176, v177 offset1:66
	s_waitcnt vmcnt(16)
	v_mul_f32_e32 v178, v51, v178
	v_mul_f32_e32 v179, v51, v179
	ds_write2_b32 v197, v178, v179 offset0:132 offset1:198
	v_add_u32_e32 v197, 0x420, v197
	s_waitcnt lgkmcnt(0)
	s_waitcnt vmcnt(14)
	v_mul_f32_e32 v180, v51, v180
	v_mul_f32_e32 v181, v51, v181
	ds_write2_b32 v197, v180, v181 offset1:66
	s_waitcnt vmcnt(12)
	v_mul_f32_e32 v182, v51, v182
	v_mul_f32_e32 v183, v51, v183
	ds_write2_b32 v197, v182, v183 offset0:132 offset1:198
	v_add_u32_e32 v197, 0x420, v197
	s_waitcnt vmcnt(10)
	v_mul_f32_e32 v184, v51, v184
	v_mul_f32_e32 v185, v51, v185
	ds_write2_b32 v197, v184, v185 offset1:66
	s_waitcnt vmcnt(8)
	v_mul_f32_e32 v186, v51, v186
	v_mul_f32_e32 v187, v51, v187
	ds_write2_b32 v197, v186, v187 offset0:132 offset1:198
	v_add_u32_e32 v197, 0x420, v197
	s_waitcnt vmcnt(6)
	v_mul_f32_e32 v188, v51, v188
	v_mul_f32_e32 v189, v51, v189
	ds_write2_b32 v197, v188, v189 offset1:66
	s_waitcnt vmcnt(4)
	v_mul_f32_e32 v190, v51, v190
	v_mul_f32_e32 v191, v51, v191
	ds_write2_b32 v197, v190, v191 offset0:132 offset1:198
	v_add_u32_e32 v197, 0x420, v197
	s_waitcnt vmcnt(2)
	v_mul_f32_e32 v192, v51, v192
	v_mul_f32_e32 v193, v51, v193
	ds_write2_b32 v197, v192, v193 offset1:66
	s_waitcnt vmcnt(0)
	v_mul_f32_e32 v194, v51, v194
	v_mul_f32_e32 v195, v51, v195
	ds_write2_b32 v197, v194, v195 offset0:132 offset1:198
	s_branch .Le18_rd
